# gmlp mixing-matrix staging: rows preloaded at item head, rinv read once, cndmask masking
# speedup vs baseline: 1.0080x; 1.0080x over previous
; #define LAS __attribute__((address_space(3)))
; __device__ __forceinline__ void gmlp_gate_phase(const Params& p, LAS unsigned char* lds, bf16_t* U, const bf16_t* V, const float* ssv, const int tid, const int bx) {
;     ...
;         for (int i = 0; i < 8; ++i) { const int pc = tid + 512 * i, s = pc >> 5, d0 = (pc & 31) * 8;
;             const u32x4 v = *(const u32x4*)(V + (size_t)(tok0 + s) * 2048 + colb + d0);
;             LAS unsigned* dst = (LAS unsigned*)(Vs + s * 258 + d0); dst[0] = v.x; dst[1] = v.y; dst[2] = v.z; dst[3] = v.w; }
;         __syncthreads();
;         f32x4 acc[8][2]; u32x2 upre[8][2];
; #pragma unroll
;         for (int mb = 0; mb < 8; ++mb) { acc[mb][0] = (f32x4){0.f, 0.f, 0.f, 0.f}; acc[mb][1] = (f32x4){0.f, 0.f, 0.f, 0.f};
; #pragma unroll
;             for (int nb = 0; nb < 2; ++nb) upre[mb][nb] = *(const u32x2*)(U + (size_t)(tok0 + mb * 16 + fr) * 2048 + colb + wave * 32 + nb * 16 + 4 * fq); }
; #pragma unroll
;         for (int kk = 0; kk < 4; ++kk) {
;             bf16x8 vf[2];
; #pragma unroll
;             for (int nb = 0; nb < 2; ++nb) { const int d = wave * 32 + nb * 16 + fr;
; #pragma unroll
;                 for (int j = 0; j < 8; ++j) vf[nb][j] = (short)Vs[(kk * 32 + fq * 8 + j) * 258 + d]; }
; #pragma unroll
;             for (int mb = 0; mb < 8; ++mb) { if (32 * kk <= 16 * mb + 15) {
;                 const bf16x8 wf = *(const LAS bf16x8*)(Wm + (mb * 16 + fr) * 136 + kk * 32 + fq * 8);
;                 acc[mb][0] = __builtin_amdgcn_mfma_f32_16x16x32_bf16(vf[0], wf, acc[mb][0], 0, 0, 0);
;                 acc[mb][1] = __builtin_amdgcn_mfma_f32_16x16x32_bf16(vf[1], wf, acc[mb][1], 0, 0, 0); } }
.LBB0_78:
	s_lshl_b32 s0, s72, 9
	s_and_b32 s1, s3, 0x100
	s_or_b32 s0, s0, s1
	s_lshl_b32 s72, s0, 1
	s_mov_b32 s73, s93
	v_lshl_add_u64 v[6:7], v[74:75], 0, s[72:73]
	v_add_u32_e32 v8, 0x8800, v169
	s_waitcnt vmcnt(0)
	ds_write2_b32 v8, v86, v87 offset1:1
	v_add_u32_e32 v2, 0x8808, v169
	ds_write2_b32 v2, v88, v89 offset1:1
	v_add_u32_e32 v8, 0x8800, v170
	ds_write2_b32 v8, v90, v91 offset1:1
	v_add_u32_e32 v2, 0x8808, v170
	ds_write2_b32 v2, v92, v93 offset1:1
	v_add_u32_e32 v8, 0x8800, v171
	ds_write2_b32 v8, v94, v95 offset1:1
	v_add_u32_e32 v2, 0x8808, v171
	ds_write2_b32 v2, v96, v97 offset1:1
	v_add_u32_e32 v8, 0x8800, v172
	ds_write2_b32 v8, v98, v99 offset1:1
	v_add_u32_e32 v2, 0x8808, v172
	ds_write2_b32 v2, v100, v101 offset1:1
	v_add_u32_e32 v8, 0x8800, v173
	ds_write2_b32 v8, v102, v103 offset1:1
	v_add_u32_e32 v2, 0x8808, v173
	ds_write2_b32 v2, v104, v105 offset1:1
	v_add_u32_e32 v8, 0x8800, v174
	ds_write2_b32 v8, v106, v107 offset1:1
	v_add_u32_e32 v2, 0x8808, v174
	ds_write2_b32 v2, v108, v109 offset1:1
	v_add_u32_e32 v8, 0x8800, v175
	ds_write2_b32 v8, v110, v111 offset1:1
	v_add_u32_e32 v2, 0x8808, v175
	ds_write2_b32 v2, v112, v113 offset1:1
	v_add_u32_e32 v6, 0x8800, v176
	ds_write2_b32 v6, v114, v115 offset1:1
	v_add_u32_e32 v2, 0x8808, v176
	ds_write2_b32 v2, v116, v117 offset1:1
	v_or_b32_e32 v4, s85, v138
	v_ashrrev_i32_e32 v5, 31, v4
	v_lshl_add_u64 v[2:3], v[76:77], 0, s[72:73]
	v_lshlrev_b64 v[66:67], 12, v[4:5]
	v_lshl_add_u64 v[4:5], v[2:3], 0, v[66:67]
	s_waitcnt lgkmcnt(0)
	s_barrier
	global_load_dwordx2 v[134:135], v[4:5], off
	global_load_dwordx2 v[130:131], v[4:5], off offset:32
	v_or_b32_e32 v4, s85, v158
	v_ashrrev_i32_e32 v5, 31, v4
	v_lshlrev_b64 v[128:129], 12, v[4:5]
	v_lshl_add_u64 v[4:5], v[2:3], 0, v[128:129]
	global_load_dwordx2 v[126:127], v[4:5], off
	global_load_dwordx2 v[124:125], v[4:5], off offset:32
	v_or_b32_e32 v4, s85, v159
	v_ashrrev_i32_e32 v5, 31, v4
	v_lshlrev_b64 v[122:123], 12, v[4:5]
	v_lshl_add_u64 v[4:5], v[2:3], 0, v[122:123]
	global_load_dwordx2 v[120:121], v[4:5], off
	global_load_dwordx2 v[118:119], v[4:5], off offset:32
	v_or_b32_e32 v4, s85, v160
	v_ashrrev_i32_e32 v5, 31, v4
	v_lshlrev_b64 v[116:117], 12, v[4:5]
	v_lshl_add_u64 v[4:5], v[2:3], 0, v[116:117]
	global_load_dwordx2 v[114:115], v[4:5], off
	global_load_dwordx2 v[112:113], v[4:5], off offset:32
	v_or_b32_e32 v4, s85, v161
	v_ashrrev_i32_e32 v5, 31, v4
	v_lshlrev_b64 v[110:111], 12, v[4:5]
	v_lshl_add_u64 v[4:5], v[2:3], 0, v[110:111]
	global_load_dwordx2 v[108:109], v[4:5], off
	global_load_dwordx2 v[106:107], v[4:5], off offset:32
	v_or_b32_e32 v4, s85, v162
	v_ashrrev_i32_e32 v5, 31, v4
	v_lshlrev_b64 v[104:105], 12, v[4:5]
	v_lshl_add_u64 v[4:5], v[2:3], 0, v[104:105]
	global_load_dwordx2 v[102:103], v[4:5], off
	global_load_dwordx2 v[100:101], v[4:5], off offset:32
	v_or_b32_e32 v4, s85, v163
	v_ashrrev_i32_e32 v5, 31, v4
	v_lshlrev_b64 v[98:99], 12, v[4:5]
	v_lshl_add_u64 v[4:5], v[2:3], 0, v[98:99]
	global_load_dwordx2 v[96:97], v[4:5], off
	global_load_dwordx2 v[92:93], v[4:5], off offset:32
	v_or_b32_e32 v4, s78, v164
	v_ashrrev_i32_e32 v5, 31, v4
	v_lshlrev_b64 v[90:91], 12, v[4:5]
	v_lshl_add_u64 v[2:3], v[2:3], 0, v[90:91]
	global_load_dwordx2 v[88:89], v[2:3], off
	global_load_dwordx2 v[86:87], v[2:3], off offset:32
	ds_read_u16 v2, v177 offset:35332
	ds_read_u16 v3, v177 offset:35848
	ds_read_u16 v6, v177 offset:36364
	ds_read_u16 v4, v177 offset:36880
	ds_read_u16 v7, v177 offset:37396
	ds_read_u16 v5, v177 offset:37912
	ds_read_u16 v8, v177 offset:38428
	ds_read_u16 v9, v177 offset:34816
	ds_read_u16 v10, v177 offset:34848
	ds_read_u16 v11, v177 offset:35364
	ds_read_u16 v12, v177 offset:35880
	ds_read_u16 v13, v177 offset:36396
	ds_read_u16 v14, v177 offset:36912
	ds_read_u16 v15, v177 offset:37428
	ds_read_u16 v16, v177 offset:37944
	ds_read_u16 v17, v177 offset:38460
	s_waitcnt lgkmcnt(0)
	v_perm_b32 v5, v8, v5, s33
	v_perm_b32 v4, v7, v4, s33
	v_perm_b32 v3, v6, v3, s33
	v_perm_b32 v2, v2, v9, s33
	v_perm_b32 v9, v17, v16, s33
	v_perm_b32 v8, v15, v14, s33
	v_perm_b32 v7, v13, v12, s33
	v_perm_b32 v6, v11, v10, s33
	ds_read_b128 v[10:13], v178
	ds_read_b128 v[18:21], v178 offset:13056
	s_waitcnt lgkmcnt(0)
	v_mfma_f32_16x16x32_bf16 v[62:65], v[2:5], v[10:13], 0
	ds_read_b128 v[26:29], v178 offset:17408
	ds_read_b128 v[34:37], v178 offset:21760
	v_readlane_b32 s72, v253, 53
	v_mfma_f32_16x16x32_bf16 v[58:61], v[6:9], v[10:13], 0
	ds_read_b128 v[10:13], v178 offset:4352
	v_readlane_b32 s73, v253, 54
	v_readlane_b32 s74, v253, 55
	s_waitcnt lgkmcnt(0)
	v_mfma_f32_16x16x32_bf16 v[54:57], v[2:5], v[10:13], 0
	v_readlane_b32 s75, v253, 56
	v_mfma_f32_16x16x32_bf16 v[50:53], v[6:9], v[10:13], 0
	ds_read_b128 v[10:13], v178 offset:8704
	v_mfma_f32_16x16x32_bf16 v[204:207], v[2:5], v[34:37], 0
	v_mfma_f32_16x16x32_bf16 v[208:211], v[6:9], v[34:37], 0
	ds_read_b128 v[34:37], v178 offset:26112
	s_waitcnt lgkmcnt(0)
	v_mfma_f32_16x16x32_bf16 v[212:215], v[2:5], v[34:37], 0
	v_mfma_f32_16x16x32_bf16 v[216:219], v[6:9], v[34:37], 0
	ds_read_b128 v[34:37], v178 offset:30464
	v_mfma_f32_16x16x32_bf16 v[14:17], v[2:5], v[10:13], 0
	v_mfma_f32_16x16x32_bf16 v[10:13], v[6:9], v[10:13], 0
	v_mfma_f32_16x16x32_bf16 v[22:25], v[2:5], v[18:21], 0
	v_mfma_f32_16x16x32_bf16 v[18:21], v[6:9], v[18:21], 0
	v_mfma_f32_16x16x32_bf16 v[30:33], v[2:5], v[26:29], 0
	v_mfma_f32_16x16x32_bf16 v[26:29], v[6:9], v[26:29], 0
	s_waitcnt lgkmcnt(0)
; #define LAS __attribute__((address_space(3)))
; __device__ __forceinline__ unsigned cvt_pk_bf16(float lo, float hi) { unsigned r; asm("v_cvt_pk_bf16_f32 %0, %1, %2" : "=v"(r) : "v"(lo), "v"(hi)); return r; }
; __device__ __forceinline__ float bf_lo(unsigned w) { return __uint_as_float(w << 16); }
; __device__ __forceinline__ float bf_hi(unsigned w) { return __uint_as_float(w & 0xffff0000u); }
; __device__ __forceinline__ void gmlp_gate_phase(const Params& p, LAS unsigned char* lds, bf16_t* U, const bf16_t* V, const float* ssv, const int tid, const int bx) {
;     ...
;         for (int kk = 0; kk < 4; ++kk) {
;             bf16x8 vf[2];
; #pragma unroll
;             for (int nb = 0; nb < 2; ++nb) { const int d = wave * 32 + nb * 16 + fr;
; #pragma unroll
;                 for (int j = 0; j < 8; ++j) vf[nb][j] = (short)Vs[(kk * 32 + fq * 8 + j) * 258 + d]; }
; #pragma unroll
;             for (int mb = 0; mb < 8; ++mb) { if (32 * kk <= 16 * mb + 15) {
;                 const bf16x8 wf = *(const LAS bf16x8*)(Wm + (mb * 16 + fr) * 136 + kk * 32 + fq * 8);
;                 acc[mb][0] = __builtin_amdgcn_mfma_f32_16x16x32_bf16(vf[0], wf, acc[mb][0], 0, 0, 0);
;                 acc[mb][1] = __builtin_amdgcn_mfma_f32_16x16x32_bf16(vf[1], wf, acc[mb][1], 0, 0, 0); } }
;         }
; #pragma unroll
;         for (int mb = 0; mb < 8; ++mb) { const int t = mb * 16 + fr; const float bs = b_s[g * 128 + t];
; #pragma unroll
;             for (int nb = 0; nb < 2; ++nb) { const int col = colb + wave * 32 + nb * 16 + 4 * fq;
;                 const f32x4 gg = *(const f32x4*)(gv + col); bf16_t* up = U + (size_t)(tok0 + t) * 2048 + col;
;                 const u32x2 uw = upre[mb][nb];
;                 const float o0 = bf_lo(uw.x) * (acc[mb][nb][0] * gg[0] + bs), o1 = bf_hi(uw.x) * (acc[mb][nb][1] * gg[1] + bs), o2 = bf_lo(uw.y) * (acc[mb][nb][2] * gg[2] + bs), o3 = bf_hi(uw.y) * (acc[mb][nb][3] * gg[3] + bs);
;                 u32x2 ow; ow.x = cvt_pk_bf16(o0, o1); ow.y = cvt_pk_bf16(o2, o3); *(u32x2*)up = ow; } }
	v_mfma_f32_16x16x32_bf16 v[2:5], v[2:5], v[34:37], 0
	v_mfma_f32_16x16x32_bf16 v[6:9], v[6:9], v[34:37], 0
	ds_read_u16 v34, v177 offset:51328
	ds_read_u16 v35, v177 offset:51844
	ds_read_u16 v36, v177 offset:52360
	ds_read_u16 v37, v177 offset:52876
	ds_read_u16 v38, v177 offset:53392
	ds_read_u16 v39, v177 offset:53908
	ds_read_u16 v40, v177 offset:54424
	ds_read_u16 v41, v177 offset:54940
	ds_read_u16 v42, v177 offset:51360
	ds_read_u16 v43, v177 offset:51876
	ds_read_u16 v44, v177 offset:52392
	ds_read_u16 v45, v177 offset:52908
	ds_read_u16 v46, v177 offset:53424
	ds_read_u16 v47, v177 offset:53940
	ds_read_u16 v48, v177 offset:54456
	ds_read_u16 v49, v177 offset:54972
	s_waitcnt lgkmcnt(0)
	v_perm_b32 v221, v37, v36, s33
	v_perm_b32 v220, v35, v34, s33
	v_perm_b32 v226, v47, v46, s33
	v_perm_b32 v225, v45, v44, s33
	v_perm_b32 v227, v49, v48, s33
	v_perm_b32 v224, v43, v42, s33
	ds_read_b128 v[34:37], v178 offset:8768
	v_perm_b32 v223, v41, v40, s33
	v_perm_b32 v222, v39, v38, s33
	s_waitcnt lgkmcnt(0)
	v_mfma_f32_16x16x32_bf16 v[42:45], v[224:227], v[34:37], v[10:13]
	s_nop 2
	ds_read_b128 v[10:13], v178 offset:13120
	v_mfma_f32_16x16x32_bf16 v[46:49], v[220:223], v[34:37], v[14:17]
	s_waitcnt lgkmcnt(0)
	v_mfma_f32_16x16x32_bf16 v[38:41], v[220:223], v[10:13], v[22:25]
	v_mfma_f32_16x16x32_bf16 v[34:37], v[224:227], v[10:13], v[18:21]
	ds_read_b128 v[10:13], v178 offset:17472
	s_nop 1
	ds_read_b128 v[18:21], v178 offset:21824
	s_waitcnt lgkmcnt(0)
	v_mfma_f32_16x16x32_bf16 v[14:17], v[220:223], v[10:13], v[30:33]
	v_mfma_f32_16x16x32_bf16 v[10:13], v[224:227], v[10:13], v[26:29]
	s_nop 2
	ds_read_b128 v[26:29], v178 offset:26176
	v_mfma_f32_16x16x32_bf16 v[22:25], v[220:223], v[18:21], v[204:207]
	v_mfma_f32_16x16x32_bf16 v[18:21], v[224:227], v[18:21], v[208:211]
	s_waitcnt lgkmcnt(0)
	v_mfma_f32_16x16x32_bf16 v[204:207], v[220:223], v[26:29], v[212:215]
	v_mfma_f32_16x16x32_bf16 v[208:211], v[224:227], v[26:29], v[216:219]
	ds_read_b128 v[26:29], v178 offset:30528
	s_waitcnt lgkmcnt(0)
	v_mfma_f32_16x16x32_bf16 v[2:5], v[220:223], v[26:29], v[2:5]
	v_mfma_f32_16x16x32_bf16 v[6:9], v[224:227], v[26:29], v[6:9]
	ds_read_u16 v26, v179 offset:34816
	ds_read_u16 v27, v179 offset:34848
	ds_read_u16 v28, v180 offset:34816
	ds_read_u16 v29, v180 offset:34848
	ds_read_u16 v30, v181 offset:34816
	ds_read_u16 v31, v181 offset:34848
	ds_read_u16 v32, v182 offset:34816
	ds_read_u16 v33, v182 offset:34848
	ds_read_u16 v68, v183 offset:34816
	ds_read_u16 v69, v183 offset:34848
	ds_read_u16 v94, v184 offset:34816
	ds_read_u16 v95, v184 offset:34848
	ds_read_u16 v132, v185 offset:34816
	ds_read_u16 v133, v185 offset:34848
	ds_read_u16 v136, v186 offset:34816
	ds_read_u16 v137, v186 offset:34848
	s_waitcnt lgkmcnt(0)
	v_perm_b32 v214, v94, v68, s33
	v_perm_b32 v213, v32, v30, s33
	v_perm_b32 v212, v28, v26, s33
	v_perm_b32 v215, v136, v132, s33
	v_perm_b32 v219, v137, v133, s33
	v_perm_b32 v218, v95, v69, s33
	v_perm_b32 v217, v33, v31, s33
	v_perm_b32 v216, v29, v27, s33
	ds_read_b128 v[26:29], v178 offset:17536
	s_waitcnt lgkmcnt(0)
	v_mfma_f32_16x16x32_bf16 v[30:33], v[212:215], v[26:29], v[14:17]
	v_mfma_f32_16x16x32_bf16 v[26:29], v[216:219], v[26:29], v[10:13]
	s_nop 2
	ds_read_b128 v[10:13], v178 offset:21888
	s_waitcnt lgkmcnt(0)
	v_mfma_f32_16x16x32_bf16 v[22:25], v[212:215], v[10:13], v[22:25]
	v_mfma_f32_16x16x32_bf16 v[18:21], v[216:219], v[10:13], v[18:21]
	ds_read_b128 v[10:13], v178 offset:26240
	s_waitcnt lgkmcnt(0)
	v_mfma_f32_16x16x32_bf16 v[14:17], v[212:215], v[10:13], v[204:207]
	s_nop 2
	ds_read_b128 v[204:207], v178 offset:30592
	s_waitcnt lgkmcnt(0)
	v_mfma_f32_16x16x32_bf16 v[2:5], v[212:215], v[204:207], v[2:5]
	v_mfma_f32_16x16x32_bf16 v[204:207], v[216:219], v[204:207], v[6:9]
	s_nop 2
	ds_read_u16 v6, v187 offset:34816
	ds_read_u16 v68, v187 offset:34848
	ds_read_u16 v69, v188 offset:34816
	ds_read_u16 v94, v188 offset:34848
	ds_read_u16 v7, v189 offset:34816
	ds_read_u16 v95, v189 offset:34848
	ds_read_u16 v132, v190 offset:34816
	ds_read_u16 v133, v190 offset:34848
	ds_read_u16 v8, v191 offset:34816
	ds_read_u16 v136, v191 offset:34848
	ds_read_u16 v137, v192 offset:34816
	ds_read_u16 v194, v192 offset:34848
	ds_read_u16 v9, v193 offset:34816
	ds_read_u16 v195, v193 offset:34848
	ds_read_u16 v196, v202 offset:34816
	ds_read_u16 v197, v202 offset:34848
	s_waitcnt lgkmcnt(0)
	v_perm_b32 v7, v132, v7, s33
	v_add_u32_e32 v132, s0, v143
	v_mfma_f32_16x16x32_bf16 v[10:13], v[216:219], v[10:13], v[208:211]
	v_readlane_b32 s0, v253, 47
	v_readlane_b32 s1, v253, 48
	v_perm_b32 v8, v137, v8, s33
	v_perm_b32 v209, v133, v95, s33
	v_perm_b32 v208, v94, v68, s33
	v_ashrrev_i32_e32 v133, 31, v132
	v_or_b32_e32 v68, s92, v138
	v_lshl_add_u64 v[94:95], v[132:133], 2, s[72:73]
	v_lshlrev_b32_e32 v68, 2, v68
	v_perm_b32 v6, v69, v6, s33
	v_perm_b32 v210, v194, v136, s33
	v_lshl_add_u64 v[136:137], s[70:71], 0, v[66:67]
	v_perm_b32 v9, v196, v9, s33
	v_perm_b32 v211, v197, v195, s33
	ds_read_b128 v[212:215], v178 offset:26304
	v_lshlrev_b64 v[132:133], 1, v[132:133]
	s_waitcnt vmcnt(0)
	v_lshlrev_b32_e32 v195, 16, v134
	v_lshl_add_u64 v[136:137], v[136:137], 0, v[132:133]
	s_waitcnt lgkmcnt(0)
	v_mfma_f32_16x16x32_bf16 v[14:17], v[6:9], v[212:215], v[14:17]
	v_fma_f32 v62, v62, v228, v236
	v_and_b32_e32 v66, 0xffff0000, v134
	v_fma_f32 v63, v63, v229, v236
	v_mul_f32_e32 v63, v63, v66
	v_lshlrev_b32_e32 v66, 16, v135
	v_fma_f32 v64, v64, v230, v236
	v_mul_f32_e32 v62, v62, v195
	v_mul_f32_e32 v64, v64, v66
	v_and_b32_e32 v66, 0xffff0000, v135
	v_fma_f32 v65, v65, v231, v236
	v_mfma_f32_16x16x32_bf16 v[10:13], v[208:211], v[212:215], v[10:13]
	ds_read_b128 v[212:215], v203 offset:192
	v_mul_f32_e32 v65, v65, v66
	v_cvt_pk_bf16_f32 v62, v62, v63
	v_cvt_pk_bf16_f32 v63, v64, v65
	global_store_dwordx2 v[136:137], v[62:63], off
	v_lshlrev_b32_e32 v66, 16, v130
	s_waitcnt lgkmcnt(0)
; __device__ __forceinline__ unsigned cvt_pk_bf16(float lo, float hi) { unsigned r; asm("v_cvt_pk_bf16_f32 %0, %1, %2" : "=v"(r) : "v"(lo), "v"(hi)); return r; }
; __device__ __forceinline__ float bf_lo(unsigned w) { return __uint_as_float(w << 16); }
; __device__ __forceinline__ float bf_hi(unsigned w) { return __uint_as_float(w & 0xffff0000u); }
; __device__ __forceinline__ void gmlp_gate_phase(const Params& p, LAS unsigned char* lds, bf16_t* U, const bf16_t* V, const float* ssv, const int tid, const int bx) {
;     ...
;         for (int mb = 0; mb < 8; ++mb) { const int t = mb * 16 + fr; const float bs = b_s[g * 128 + t];
; #pragma unroll
;             for (int nb = 0; nb < 2; ++nb) { const int col = colb + wave * 32 + nb * 16 + 4 * fq;
;                 const f32x4 gg = *(const f32x4*)(gv + col); bf16_t* up = U + (size_t)(tok0 + t) * 2048 + col;
;                 const u32x2 uw = upre[mb][nb];
;                 const float o0 = bf_lo(uw.x) * (acc[mb][nb][0] * gg[0] + bs), o1 = bf_hi(uw.x) * (acc[mb][nb][1] * gg[1] + bs), o2 = bf_lo(uw.y) * (acc[mb][nb][2] * gg[2] + bs), o3 = bf_hi(uw.y) * (acc[mb][nb][3] * gg[3] + bs);
;                 u32x2 ow; ow.x = cvt_pk_bf16(o0, o1); ow.y = cvt_pk_bf16(o2, o3); *(u32x2*)up = ow; } }
	v_mfma_f32_16x16x32_bf16 v[6:9], v[6:9], v[212:215], v[2:5]
	v_fma_f32 v58, v58, v232, v236
	v_and_b32_e32 v62, 0xffff0000, v130
	v_fma_f32 v59, v59, v233, v236
	v_mul_f32_e32 v58, v58, v66
	v_mul_f32_e32 v59, v59, v62
	v_lshlrev_b32_e32 v62, 16, v131
	v_fma_f32 v60, v60, v234, v236
	v_mul_f32_e32 v60, v60, v62
	v_and_b32_e32 v62, 0xffff0000, v131
	v_fmac_f32_e32 v236, v61, v235
	v_cvt_pk_bf16_f32 v58, v58, v59
	v_mul_f32_e32 v61, v236, v62
	v_cvt_pk_bf16_f32 v59, v60, v61
	global_store_dwordx2 v[136:137], v[58:59], off offset:32
	v_add_lshl_u32 v58, s92, v138, 2
	v_lshl_add_u64 v[64:65], s[70:71], 0, v[128:129]
	v_lshlrev_b32_e32 v66, 16, v126
	v_lshl_add_u64 v[64:65], v[64:65], 0, v[132:133]
	v_mfma_f32_16x16x32_bf16 v[2:5], v[208:211], v[212:215], v[204:207]
	v_fma_f32 v54, v54, v228, v237
	v_and_b32_e32 v60, 0xffff0000, v126
	v_fma_f32 v55, v55, v229, v237
	v_mul_f32_e32 v55, v55, v60
	v_lshlrev_b32_e32 v60, 16, v127
	v_fma_f32 v56, v56, v230, v237
	v_mul_f32_e32 v54, v54, v66
	v_mul_f32_e32 v56, v56, v60
	v_and_b32_e32 v60, 0xffff0000, v127
	v_fma_f32 v57, v57, v231, v237
	v_mul_f32_e32 v57, v57, v60
	v_cvt_pk_bf16_f32 v54, v54, v55
	v_cvt_pk_bf16_f32 v55, v56, v57
	global_store_dwordx2 v[64:65], v[54:55], off
	v_lshlrev_b32_e32 v60, 16, v124
	v_fma_f32 v50, v50, v232, v237
	v_and_b32_e32 v54, 0xffff0000, v124
	v_fma_f32 v51, v51, v233, v237
	v_mul_f32_e32 v51, v51, v54
	v_lshlrev_b32_e32 v54, 16, v125
	v_fma_f32 v52, v52, v234, v237
	v_mul_f32_e32 v50, v50, v60
	v_mul_f32_e32 v52, v52, v54
	v_and_b32_e32 v54, 0xffff0000, v125
	v_fmac_f32_e32 v237, v53, v235
	v_mul_f32_e32 v53, v237, v54
	v_cvt_pk_bf16_f32 v50, v50, v51
	v_cvt_pk_bf16_f32 v51, v52, v53
	global_store_dwordx2 v[64:65], v[50:51], off offset:32
	v_lshl_add_u64 v[54:55], s[70:71], 0, v[122:123]
	v_lshlrev_b32_e32 v57, 16, v120
	v_lshl_add_u64 v[54:55], v[54:55], 0, v[132:133]
	v_fma_f32 v46, v46, v228, v238
	v_and_b32_e32 v50, 0xffff0000, v120
	v_fma_f32 v47, v47, v229, v238
	v_mul_f32_e32 v47, v47, v50
	v_lshlrev_b32_e32 v50, 16, v121
	v_fma_f32 v48, v48, v230, v238
	v_mul_f32_e32 v46, v46, v57
	v_mul_f32_e32 v48, v48, v50
	v_and_b32_e32 v50, 0xffff0000, v121
	v_fma_f32 v49, v49, v231, v238
	v_mul_f32_e32 v49, v49, v50
	v_cvt_pk_bf16_f32 v46, v46, v47
	v_cvt_pk_bf16_f32 v47, v48, v49
	global_store_dwordx2 v[54:55], v[46:47], off
	v_lshlrev_b32_e32 v50, 16, v118
	v_fma_f32 v42, v42, v232, v238
	v_and_b32_e32 v46, 0xffff0000, v118
	v_fma_f32 v43, v43, v233, v238
	v_mul_f32_e32 v43, v43, v46
	v_lshlrev_b32_e32 v46, 16, v119
	v_fma_f32 v44, v44, v234, v238
	v_mul_f32_e32 v42, v42, v50
	v_mul_f32_e32 v44, v44, v46
	v_and_b32_e32 v46, 0xffff0000, v119
	v_fmac_f32_e32 v238, v45, v235
	v_mul_f32_e32 v45, v238, v46
	v_cvt_pk_bf16_f32 v42, v42, v43
	v_cvt_pk_bf16_f32 v43, v44, v45
	global_store_dwordx2 v[54:55], v[42:43], off offset:32
	v_lshl_add_u64 v[46:47], s[70:71], 0, v[116:117]
	v_lshlrev_b32_e32 v49, 16, v114
	v_lshl_add_u64 v[46:47], v[46:47], 0, v[132:133]
	v_fma_f32 v38, v38, v228, v239
	v_and_b32_e32 v42, 0xffff0000, v114
	v_fma_f32 v39, v39, v229, v239
	v_mul_f32_e32 v39, v39, v42
	v_lshlrev_b32_e32 v42, 16, v115
	v_fma_f32 v40, v40, v230, v239
	v_mul_f32_e32 v38, v38, v49
	v_mul_f32_e32 v40, v40, v42
	v_and_b32_e32 v42, 0xffff0000, v115
	v_fma_f32 v41, v41, v231, v239
	v_mul_f32_e32 v41, v41, v42
	v_cvt_pk_bf16_f32 v38, v38, v39
	v_cvt_pk_bf16_f32 v39, v40, v41
	global_store_dwordx2 v[46:47], v[38:39], off
	v_lshlrev_b32_e32 v42, 16, v112
	v_fma_f32 v34, v34, v232, v239
	v_and_b32_e32 v38, 0xffff0000, v112
	v_fma_f32 v35, v35, v233, v239
	v_mul_f32_e32 v35, v35, v38
	v_lshlrev_b32_e32 v38, 16, v113
	v_fma_f32 v36, v36, v234, v239
	v_mul_f32_e32 v34, v34, v42
	v_mul_f32_e32 v36, v36, v38
	v_and_b32_e32 v38, 0xffff0000, v113
	v_fmac_f32_e32 v239, v37, v235
	v_mul_f32_e32 v37, v239, v38
	v_cvt_pk_bf16_f32 v34, v34, v35
	v_cvt_pk_bf16_f32 v35, v36, v37
	global_store_dwordx2 v[46:47], v[34:35], off offset:32
	v_lshl_add_u64 v[38:39], s[70:71], 0, v[110:111]
	v_lshlrev_b32_e32 v41, 16, v108
	v_lshl_add_u64 v[38:39], v[38:39], 0, v[132:133]
	v_fma_f32 v30, v30, v228, v198
	v_and_b32_e32 v34, 0xffff0000, v108
	v_fma_f32 v31, v31, v229, v198
	v_mul_f32_e32 v31, v31, v34
	v_lshlrev_b32_e32 v34, 16, v109
	v_fma_f32 v32, v32, v230, v198
	v_mul_f32_e32 v30, v30, v41
	v_mul_f32_e32 v32, v32, v34
	v_and_b32_e32 v34, 0xffff0000, v109
	v_fma_f32 v33, v33, v231, v198
	v_mul_f32_e32 v33, v33, v34
	v_cvt_pk_bf16_f32 v30, v30, v31
	v_cvt_pk_bf16_f32 v31, v32, v33
	global_store_dwordx2 v[38:39], v[30:31], off
	v_lshlrev_b32_e32 v34, 16, v106
	v_fma_f32 v26, v26, v232, v198
	v_and_b32_e32 v30, 0xffff0000, v106
	v_fma_f32 v27, v27, v233, v198
	v_mul_f32_e32 v27, v27, v30
	v_lshlrev_b32_e32 v30, 16, v107
	v_fma_f32 v28, v28, v234, v198
	v_mul_f32_e32 v26, v26, v34
	v_mul_f32_e32 v28, v28, v30
	v_and_b32_e32 v30, 0xffff0000, v107
	v_fmac_f32_e32 v198, v29, v235
	v_mul_f32_e32 v29, v198, v30
	v_cvt_pk_bf16_f32 v26, v26, v27
	v_cvt_pk_bf16_f32 v27, v28, v29
	global_store_dwordx2 v[38:39], v[26:27], off offset:32
	v_lshl_add_u64 v[30:31], s[70:71], 0, v[104:105]
	v_lshlrev_b32_e32 v33, 16, v102
	v_lshl_add_u64 v[30:31], v[30:31], 0, v[132:133]
	v_fma_f32 v22, v22, v228, v199
	v_and_b32_e32 v26, 0xffff0000, v102
	v_fma_f32 v23, v23, v229, v199
	v_mul_f32_e32 v23, v23, v26
	v_lshlrev_b32_e32 v26, 16, v103
	v_fma_f32 v24, v24, v230, v199
	v_mul_f32_e32 v22, v22, v33
	v_mul_f32_e32 v24, v24, v26
	v_and_b32_e32 v26, 0xffff0000, v103
	v_fma_f32 v25, v25, v231, v199
	v_mul_f32_e32 v25, v25, v26
	v_cvt_pk_bf16_f32 v22, v22, v23
	v_cvt_pk_bf16_f32 v23, v24, v25
	global_store_dwordx2 v[30:31], v[22:23], off
; #define LAS __attribute__((address_space(3)))
; __device__ __forceinline__ void gmlp_gate_phase(const Params& p, LAS unsigned char* lds, bf16_t* U, const bf16_t* V, const float* ssv, const int tid, const int bx) {
;     ...
;     for (int item = bx; item < 2048; item += gridDim.x) {
;         const int chunk = item >> 3, g = (item >> 1) & 3, half = item & 1;
;         const int tok0 = chunk * 128, colb = g * 512 + half * 256;
;         {
;             const float* pp = ssv + (size_t)(tok0 + (tid >> 2)) * 32 + (tid & 3) * 8; const f32x4 a = *(const f32x4*)pp, b = *(const f32x4*)(pp + 4);
;             float q = ((a[0] + a[1]) + (a[2] + a[3])) + ((b[0] + b[1]) + (b[2] + b[3])); q += __shfl_xor(q, 1); q += __shfl_xor(q, 2);
;             if ((tid & 3) == 0) Rv[tid >> 2] = rsqrtf(q * (1.0f / 2048.0f) + EPS); }
;         __syncthreads();
; #pragma unroll
;         for (int i = 0; i < 4; ++i) { const int pc = tid + 512 * i, t = pc >> 4, s0 = (pc & 15) * 8;
;             const f32x4 w0 = *(const f32x4*)(w_s + ((size_t)g * 128 + t) * 128 + s0), w1 = *(const f32x4*)(w_s + ((size_t)g * 128 + t) * 128 + s0 + 4);
;             float f[8];
; #pragma unroll
;             for (int j = 0; j < 4; ++j) { f[j] = (s0 + j <= t) ? w0[j] * Rv[s0 + j] : 0.f; f[4 + j] = (s0 + 4 + j <= t) ? w1[j] * Rv[s0 + 4 + j] : 0.f; }
;             *(LAS u32x4*)(Wm + t * 136 + s0) = pack8(f); }
; #pragma unroll
;         for (int i = 0; i < 8; ++i) { const int pc = tid + 512 * i, s = pc >> 5, d0 = (pc & 31) * 8;
;             const u32x4 v = *(const u32x4*)(V + (size_t)(tok0 + s) * 2048 + colb + d0);
;     ...
;         for (int mb = 0; mb < 8; ++mb) { const int t = mb * 16 + fr; const float bs = b_s[g * 128 + t];
; #pragma unroll
;             for (int nb = 0; nb < 2; ++nb) { const int col = colb + wave * 32 + nb * 16 + 4 * fq;
;                 const f32x4 gg = *(const f32x4*)(gv + col); bf16_t* up = U + (size_t)(tok0 + t) * 2048 + col;
;                 const u32x2 uw = upre[mb][nb];
;                 const float o0 = bf_lo(uw.x) * (acc[mb][nb][0] * gg[0] + bs), o1 = bf_hi(uw.x) * (acc[mb][nb][1] * gg[1] + bs), o2 = bf_lo(uw.y) * (acc[mb][nb][2] * gg[2] + bs), o3 = bf_hi(uw.y) * (acc[mb][nb][3] * gg[3] + bs);
;                 u32x2 ow; ow.x = cvt_pk_bf16(o0, o1); ow.y = cvt_pk_bf16(o2, o3); *(u32x2*)up = ow; } }
;         __syncthreads();
	v_lshlrev_b32_e32 v26, 16, v100
	v_fma_f32 v18, v18, v232, v199
	v_and_b32_e32 v22, 0xffff0000, v100
	v_fma_f32 v19, v19, v233, v199
	v_mul_f32_e32 v19, v19, v22
	v_lshlrev_b32_e32 v22, 16, v101
	v_fma_f32 v20, v20, v234, v199
	v_mul_f32_e32 v18, v18, v26
	v_mul_f32_e32 v20, v20, v22
	v_and_b32_e32 v22, 0xffff0000, v101
	v_fmac_f32_e32 v199, v21, v235
	v_mul_f32_e32 v21, v199, v22
	v_cvt_pk_bf16_f32 v18, v18, v19
	v_cvt_pk_bf16_f32 v19, v20, v21
	global_store_dwordx2 v[30:31], v[18:19], off offset:32
	v_lshl_add_u64 v[22:23], s[70:71], 0, v[98:99]
	v_lshlrev_b32_e32 v25, 16, v96
	v_lshl_add_u64 v[22:23], v[22:23], 0, v[132:133]
	v_fma_f32 v14, v14, v228, v151
	v_and_b32_e32 v18, 0xffff0000, v96
	v_fma_f32 v15, v15, v229, v151
	v_mul_f32_e32 v15, v15, v18
	v_lshlrev_b32_e32 v18, 16, v97
	v_fma_f32 v16, v16, v230, v151
	v_mul_f32_e32 v14, v14, v25
	v_mul_f32_e32 v16, v16, v18
	v_and_b32_e32 v18, 0xffff0000, v97
	v_fma_f32 v17, v17, v231, v151
	v_mul_f32_e32 v17, v17, v18
	v_cvt_pk_bf16_f32 v14, v14, v15
	v_cvt_pk_bf16_f32 v15, v16, v17
	global_store_dwordx2 v[22:23], v[14:15], off
	v_lshlrev_b32_e32 v18, 16, v92
	v_fma_f32 v10, v10, v232, v151
	v_and_b32_e32 v14, 0xffff0000, v92
	v_fma_f32 v11, v11, v233, v151
	v_mul_f32_e32 v11, v11, v14
	v_lshlrev_b32_e32 v14, 16, v93
	v_fma_f32 v12, v12, v234, v151
	v_mul_f32_e32 v10, v10, v18
	v_mul_f32_e32 v12, v12, v14
	v_and_b32_e32 v14, 0xffff0000, v93
	v_fmac_f32_e32 v151, v13, v235
	v_mul_f32_e32 v13, v151, v14
	v_cvt_pk_bf16_f32 v10, v10, v11
	v_cvt_pk_bf16_f32 v11, v12, v13
	global_store_dwordx2 v[22:23], v[10:11], off offset:32
	v_lshl_add_u64 v[14:15], s[70:71], 0, v[90:91]
	v_lshlrev_b32_e32 v17, 16, v88
	v_lshl_add_u64 v[14:15], v[14:15], 0, v[132:133]
	v_readlane_b32 s0, v254, 8
	s_add_i32 s79, s79, s0
	v_readlane_b32 s0, v253, 39
	s_add_i32 s3, s3, s0
	v_readlane_b32 s0, v253, 40
	s_add_i32 s78, s78, s0
	s_cmpk_gt_i32 s79, 0x7ff
	v_readlane_b32 s1, v254, 9
	v_fma_f32 v6, v6, v228, v152
	v_and_b32_e32 v10, 0xffff0000, v88
	v_fma_f32 v7, v7, v229, v152
	v_mul_f32_e32 v7, v7, v10
	v_lshlrev_b32_e32 v10, 16, v89
	v_fma_f32 v8, v8, v230, v152
	v_mul_f32_e32 v6, v6, v17
	v_mul_f32_e32 v8, v8, v10
	v_and_b32_e32 v10, 0xffff0000, v89
	v_fma_f32 v9, v9, v231, v152
	v_mul_f32_e32 v9, v9, v10
	v_cvt_pk_bf16_f32 v6, v6, v7
	v_cvt_pk_bf16_f32 v7, v8, v9
	global_store_dwordx2 v[14:15], v[6:7], off
	v_lshlrev_b32_e32 v10, 16, v86
	v_fma_f32 v2, v2, v232, v152
	v_and_b32_e32 v6, 0xffff0000, v86
	v_fma_f32 v3, v3, v233, v152
	v_mul_f32_e32 v3, v3, v6
	v_lshlrev_b32_e32 v6, 16, v87
	v_fma_f32 v4, v4, v234, v152
	v_mul_f32_e32 v2, v2, v10
	v_mul_f32_e32 v4, v4, v6
	v_and_b32_e32 v6, 0xffff0000, v87
	v_fmac_f32_e32 v152, v5, v235
	v_mul_f32_e32 v5, v152, v6
	v_cvt_pk_bf16_f32 v2, v2, v3
	v_cvt_pk_bf16_f32 v3, v4, v5
	global_store_dwordx2 v[14:15], v[2:3], off offset:32
	s_waitcnt lgkmcnt(0)
	s_barrier
	s_cbranch_scc1 .LBB0_145
.LBB0_79:
	s_and_b32 s85, s78, 0xffffff80
	v_add_u32_e32 v2, s85, v139
	v_ashrrev_i32_e32 v3, 31, v2
	v_lshlrev_b64 v[2:3], 7, v[2:3]
	v_lshl_add_u64 v[6:7], v[70:71], 0, v[2:3]
	global_load_dwordx4 v[2:5], v[6:7], off
	s_nop 0
	global_load_dwordx4 v[6:9], v[6:7], off offset:16
	s_bfe_u32 s98, s79, 0x20001
	s_lshl_b32 s98, s98, 9
	s_and_b32 s99, s3, 0x100
	s_or_b32 s98, s98, s99
	v_add_u32_e32 v118, s98, v143
	s_lshl_b32 s98, s98, 1
	s_mov_b32 s99, 0
	v_lshl_add_u64 v[120:121], v[74:75], 0, s[98:99]
	s_add_i32 s98, s85, 0
	v_add_u32_e32 v122, s98, v150
	v_ashrrev_i32_e32 v123, 31, v122
	v_lshlrev_b64 v[122:123], 12, v[122:123]
	v_lshl_add_u64 v[122:123], v[120:121], 0, v[122:123]
	global_load_dwordx4 v[86:89], v[122:123], off
	s_add_i32 s98, s85, 16
	v_add_u32_e32 v122, s98, v150
	v_ashrrev_i32_e32 v123, 31, v122
	v_lshlrev_b64 v[122:123], 12, v[122:123]
	v_lshl_add_u64 v[122:123], v[120:121], 0, v[122:123]
	global_load_dwordx4 v[90:93], v[122:123], off
	s_add_i32 s98, s85, 32
	v_add_u32_e32 v122, s98, v150
	v_ashrrev_i32_e32 v123, 31, v122
	v_lshlrev_b64 v[122:123], 12, v[122:123]
	v_lshl_add_u64 v[122:123], v[120:121], 0, v[122:123]
	global_load_dwordx4 v[94:97], v[122:123], off
	s_add_i32 s98, s85, 48
	v_add_u32_e32 v122, s98, v150
	v_ashrrev_i32_e32 v123, 31, v122
	v_lshlrev_b64 v[122:123], 12, v[122:123]
	v_lshl_add_u64 v[122:123], v[120:121], 0, v[122:123]
	global_load_dwordx4 v[98:101], v[122:123], off
	s_add_i32 s98, s85, 64
	v_add_u32_e32 v122, s98, v150
	v_ashrrev_i32_e32 v123, 31, v122
	v_lshlrev_b64 v[122:123], 12, v[122:123]
	v_lshl_add_u64 v[122:123], v[120:121], 0, v[122:123]
	global_load_dwordx4 v[102:105], v[122:123], off
	s_add_i32 s98, s85, 80
	v_add_u32_e32 v122, s98, v150
	v_ashrrev_i32_e32 v123, 31, v122
	v_lshlrev_b64 v[122:123], 12, v[122:123]
	v_lshl_add_u64 v[122:123], v[120:121], 0, v[122:123]
	global_load_dwordx4 v[106:109], v[122:123], off
	s_add_i32 s98, s85, 96
	v_add_u32_e32 v122, s98, v150
	v_ashrrev_i32_e32 v123, 31, v122
	v_lshlrev_b64 v[122:123], 12, v[122:123]
	v_lshl_add_u64 v[122:123], v[120:121], 0, v[122:123]
	global_load_dwordx4 v[110:113], v[122:123], off
	s_add_i32 s98, s85, 112
	v_add_u32_e32 v122, s98, v150
	v_ashrrev_i32_e32 v123, 31, v122
	v_lshlrev_b64 v[122:123], 12, v[122:123]
	v_lshl_add_u64 v[122:123], v[120:121], 0, v[122:123]
	global_load_dwordx4 v[114:117], v[122:123], off
	s_bfe_u32 s98, s79, 0x20001
	s_lshl_b32 s98, s98, 7
	v_add_lshl_u32 v119, s98, v138, 2
	v_lshl_add_u64 v[122:123], s[98:99], 0, v[78:79]
	v_lshlrev_b64 v[122:123], 9, v[122:123]
; #define LAS __attribute__((address_space(3)))
; __device__ __forceinline__ u32x4 pack8(const float (&f)[8]) { u32x4 w; w.x = cvt_pk_bf16(f[0], f[1]); w.y = cvt_pk_bf16(f[2], f[3]); w.z = cvt_pk_bf16(f[4], f[5]); w.w = cvt_pk_bf16(f[6], f[7]); return w; }
; __device__ __forceinline__ void gmlp_gate_phase(const Params& p, LAS unsigned char* lds, bf16_t* U, const bf16_t* V, const float* ssv, const int tid, const int bx) {
;     ...
;             const float* pp = ssv + (size_t)(tok0 + (tid >> 2)) * 32 + (tid & 3) * 8; const f32x4 a = *(const f32x4*)pp, b = *(const f32x4*)(pp + 4);
;             float q = ((a[0] + a[1]) + (a[2] + a[3])) + ((b[0] + b[1]) + (b[2] + b[3])); q += __shfl_xor(q, 1); q += __shfl_xor(q, 2);
;             if ((tid & 3) == 0) Rv[tid >> 2] = rsqrtf(q * (1.0f / 2048.0f) + EPS); }
;         __syncthreads();
; #pragma unroll
;         for (int i = 0; i < 4; ++i) { const int pc = tid + 512 * i, t = pc >> 4, s0 = (pc & 15) * 8;
;             const f32x4 w0 = *(const f32x4*)(w_s + ((size_t)g * 128 + t) * 128 + s0), w1 = *(const f32x4*)(w_s + ((size_t)g * 128 + t) * 128 + s0 + 4);
;             float f[8];
; #pragma unroll
;             for (int j = 0; j < 4; ++j) { f[j] = (s0 + j <= t) ? w0[j] * Rv[s0 + j] : 0.f; f[4 + j] = (s0 + 4 + j <= t) ? w1[j] * Rv[s0 + 4 + j] : 0.f; }
;             *(LAS u32x4*)(Wm + t * 136 + s0) = pack8(f); }
	v_lshl_add_u64 v[122:123], v[72:73], 0, v[122:123]
	global_load_dwordx4 v[12:15], v[122:123], off
	global_load_dwordx4 v[16:19], v[122:123], off offset:16
	v_lshl_add_u64 v[122:123], s[98:99], 0, v[80:81]
	v_lshlrev_b64 v[122:123], 9, v[122:123]
	v_lshl_add_u64 v[122:123], v[72:73], 0, v[122:123]
	global_load_dwordx4 v[20:23], v[122:123], off
	global_load_dwordx4 v[24:27], v[122:123], off offset:16
	v_lshl_add_u64 v[122:123], s[98:99], 0, v[82:83]
	v_lshlrev_b64 v[122:123], 9, v[122:123]
	v_lshl_add_u64 v[122:123], v[72:73], 0, v[122:123]
	global_load_dwordx4 v[28:31], v[122:123], off
	global_load_dwordx4 v[32:35], v[122:123], off offset:16
	v_lshl_add_u64 v[122:123], s[98:99], 0, v[84:85]
	v_lshlrev_b64 v[122:123], 9, v[122:123]
	v_lshl_add_u64 v[122:123], v[72:73], 0, v[122:123]
	global_load_dwordx4 v[36:39], v[122:123], off
	global_load_dwordx4 v[40:43], v[122:123], off offset:16
	v_readlane_b32 s98, v253, 53
	v_readlane_b32 s99, v253, 54
	v_lshlrev_b32_e32 v118, 2, v118
	s_nop 4
	global_load_dwordx4 v[228:231], v118, s[98:99]
	global_load_dwordx4 v[232:235], v118, s[98:99] offset:64
	v_readlane_b32 s98, v253, 47
	v_readlane_b32 s99, v253, 48
	s_nop 4
	global_load_dword v236, v119, s[98:99]
	global_load_dword v237, v119, s[98:99] offset:64
	global_load_dword v238, v119, s[98:99] offset:128
	global_load_dword v239, v119, s[98:99] offset:192
	global_load_dword v198, v119, s[98:99] offset:256
	global_load_dword v199, v119, s[98:99] offset:320
	global_load_dword v151, v119, s[98:99] offset:384
	global_load_dword v152, v119, s[98:99] offset:448
	s_waitcnt vmcnt(26) lgkmcnt(0)
	v_add_f32_e32 v2, v2, v3
	v_add_f32_e32 v3, v4, v5
	v_add_f32_e32 v4, v6, v7
	v_add_f32_e32 v5, v8, v9
	v_add_f32_e32 v2, v2, v3
	v_add_f32_e32 v3, v4, v5
	v_add_f32_e32 v2, v2, v3
	ds_bpermute_b32 v3, v140, v2
	s_waitcnt lgkmcnt(0)
	v_add_f32_e32 v2, v2, v3
	ds_bpermute_b32 v3, v141, v2
	s_and_saveexec_b64 s[0:1], vcc
	s_cbranch_execz .LBB0_81
	s_waitcnt lgkmcnt(0)
	v_add_f32_e32 v2, v2, v3
	v_fmamk_f32 v2, v2, 0x3a000000, v240
	v_mul_f32_e32 v3, 0x4b800000, v2
	v_cmp_gt_f32_e64 s[72:73], s83, v2
	s_nop 1
	v_cndmask_b32_e64 v2, v2, v3, s[72:73]
	v_rsq_f32_e32 v2, v2
	s_nop 0
	v_mul_f32_e32 v3, 0x45800000, v2
	v_cndmask_b32_e64 v2, v2, v3, s[72:73]
	ds_write_b32 v142, v2
.LBB0_81:
	s_or_b64 exec, exec, s[0:1]
	s_bfe_u32 s72, s79, 0x20001
	s_lshl_b32 s92, s72, 7
	s_waitcnt lgkmcnt(0)
	s_barrier
	ds_read_b32 v2, v0
	ds_read_b32 v3, v0 offset:4
	ds_read_b32 v4, v146
	ds_read_b32 v5, v148
	ds_read_b32 v6, v144
	ds_read_b32 v7, v145
	ds_read_b32 v8, v147
	ds_read_b32 v9, v149
	s_waitcnt vmcnt(0) lgkmcnt(0)
	v_mul_f32_e32 v12, v12, v2
	v_mul_f32_e32 v16, v16, v6
	v_mul_f32_e32 v13, v13, v3
	v_mul_f32_e32 v17, v17, v7
	v_mul_f32_e32 v14, v14, v4
	v_mul_f32_e32 v18, v18, v8
	v_mul_f32_e32 v15, v15, v5
	v_mul_f32_e32 v19, v19, v9
	v_cndmask_b32_e64 v12, 0, v12, s[4:5]
	v_cndmask_b32_e64 v16, 0, v16, s[6:7]
	v_cndmask_b32_e64 v13, 0, v13, s[8:9]
	v_cndmask_b32_e64 v17, 0, v17, s[10:11]
	v_cndmask_b32_e64 v14, 0, v14, s[12:13]
	v_cndmask_b32_e64 v18, 0, v18, s[14:15]
	v_cndmask_b32_e64 v15, 0, v15, s[16:17]
	v_cndmask_b32_e64 v19, 0, v19, s[18:19]
	v_cvt_pk_bf16_f32 v12, v12, v13
	v_cvt_pk_bf16_f32 v13, v14, v15
	v_cvt_pk_bf16_f32 v14, v16, v17
	v_cvt_pk_bf16_f32 v15, v18, v19
	ds_write_b128 v165, v[12:15]
	v_mul_f32_e32 v20, v20, v2
	v_mul_f32_e32 v24, v24, v6
	v_mul_f32_e32 v21, v21, v3
	v_mul_f32_e32 v25, v25, v7
	v_mul_f32_e32 v22, v22, v4
	v_mul_f32_e32 v26, v26, v8
	v_mul_f32_e32 v23, v23, v5
	v_mul_f32_e32 v27, v27, v9
	v_cndmask_b32_e64 v20, 0, v20, s[20:21]
	v_cndmask_b32_e64 v24, 0, v24, s[22:23]
	v_cndmask_b32_e64 v21, 0, v21, s[24:25]
	v_cndmask_b32_e64 v25, 0, v25, s[26:27]
	v_cndmask_b32_e64 v22, 0, v22, s[28:29]
	v_cndmask_b32_e64 v26, 0, v26, s[30:31]
	v_cndmask_b32_e64 v23, 0, v23, s[34:35]
	v_cndmask_b32_e64 v27, 0, v27, s[36:37]
	v_cvt_pk_bf16_f32 v20, v20, v21
	v_cvt_pk_bf16_f32 v21, v22, v23
	v_cvt_pk_bf16_f32 v22, v24, v25
	v_cvt_pk_bf16_f32 v23, v26, v27
	ds_write_b128 v166, v[20:23]
	v_mul_f32_e32 v28, v28, v2
	v_mul_f32_e32 v32, v32, v6
	v_mul_f32_e32 v29, v29, v3
	v_mul_f32_e32 v33, v33, v7
	v_mul_f32_e32 v30, v30, v4
	v_mul_f32_e32 v34, v34, v8
	v_mul_f32_e32 v31, v31, v5
	v_mul_f32_e32 v35, v35, v9
	v_cndmask_b32_e64 v28, 0, v28, s[38:39]
	v_cndmask_b32_e64 v32, 0, v32, s[40:41]
	v_cndmask_b32_e64 v29, 0, v29, s[42:43]
	v_cndmask_b32_e64 v33, 0, v33, s[44:45]
	v_cndmask_b32_e64 v30, 0, v30, s[46:47]
	v_cndmask_b32_e64 v34, 0, v34, s[48:49]
	v_cndmask_b32_e64 v31, 0, v31, s[50:51]
	v_cndmask_b32_e64 v35, 0, v35, s[52:53]
	v_cvt_pk_bf16_f32 v28, v28, v29
	v_cvt_pk_bf16_f32 v29, v30, v31
	v_cvt_pk_bf16_f32 v30, v32, v33
	v_cvt_pk_bf16_f32 v31, v34, v35
	ds_write_b128 v167, v[28:31]
	v_mul_f32_e32 v36, v36, v2
	v_mul_f32_e32 v40, v40, v6
	v_mul_f32_e32 v37, v37, v3
	v_mul_f32_e32 v41, v41, v7
	v_mul_f32_e32 v38, v38, v4
	v_mul_f32_e32 v42, v42, v8
	v_mul_f32_e32 v39, v39, v5
	v_mul_f32_e32 v43, v43, v9
	v_cndmask_b32_e64 v36, 0, v36, s[54:55]
	v_cndmask_b32_e64 v40, 0, v40, s[56:57]
	v_cndmask_b32_e64 v37, 0, v37, s[58:59]
	v_cndmask_b32_e64 v41, 0, v41, s[60:61]
	v_cndmask_b32_e64 v38, 0, v38, s[62:63]
	v_cndmask_b32_e64 v42, 0, v42, s[64:65]
	v_cndmask_b32_e64 v39, 0, v39, s[66:67]
	v_cndmask_b32_e64 v43, 0, v43, s[68:69]
	v_cvt_pk_bf16_f32 v36, v36, v37
	v_cvt_pk_bf16_f32 v37, v38, v39
	v_cvt_pk_bf16_f32 v38, v40, v41
	v_cvt_pk_bf16_f32 v39, v42, v43
	ds_write_b128 v168, v[36:39]
	s_branch .LBB0_78
